# phase0b one transpose per wave: [2048,5008) to compress-GEMM idle workgroups, [5008,6928) to the w_in GEMM tail
# baseline (speedup 1.0000x reference)
.LBB0_66:
	s_add_i32 s61, s61, s71
	s_add_i32 s14, s14, s15
	s_add_i32 s16, s16, s17
	s_add_i32 s18, s18, s19
	s_cmpk_lg_i32 s76, 0x100
	s_cbranch_scc1 .Lp0b_nocomp
	s_cmpk_gt_i32 s61, 0x7ff
	s_cbranch_scc1 .LBB0_154
	s_cmpk_lt_i32 s61, 0xe00
	s_cbranch_scc1 .Lp0b_nocomp
	s_addk_i32 s61, 0xb10
	s_add_i32 s14, s14, 0x16200
	s_addk_i32 s16, 0x5880
	s_addk_i32 s18, 0x1620

.Ltail_p0b:
	s_cmpk_lg_i32 s76, 0x100
	s_cbranch_scc1 .Ltail_skip
	v_writelane_b32 v248, s0, 0
	v_writelane_b32 v248, s1, 1
	v_writelane_b32 v248, s10, 2
	v_writelane_b32 v248, s13, 3
	v_writelane_b32 v248, s27, 4
	v_writelane_b32 v248, s28, 5
	v_writelane_b32 v248, s29, 6
	v_writelane_b32 v248, s33, 7
	v_writelane_b32 v248, s42, 8
	v_writelane_b32 v248, s44, 9
	v_writelane_b32 v248, s46, 10
	v_writelane_b32 v248, s47, 11
	v_writelane_b32 v248, s48, 12
	v_writelane_b32 v248, s49, 13
	v_writelane_b32 v248, s50, 14
	v_writelane_b32 v248, s54, 15
	v_writelane_b32 v248, s55, 16
	v_writelane_b32 v248, s56, 17
	v_writelane_b32 v248, s62, 18
	v_writelane_b32 v248, s63, 19
	s_add_i32 s2, 0, 0x23fa8
	v_mov_b32_e32 v0, s2
	ds_read_b64 v[2:3], v0
	v_mbcnt_lo_u32_b32 v0, -1, 0
	v_mbcnt_hi_u32_b32 v1, -1, v0
	s_waitcnt lgkmcnt(0)
	v_readfirstlane_b32 s0, v2
	v_readfirstlane_b32 s1, v3
	s_mov_b32 s3, 0
	s_add_i32 s61, s80, 0xffffff80
	s_lshl_b32 s61, s61, 3
	s_add_i32 s61, s61, s79
	s_addk_i32 s61, 0x1390
	s_cmpk_gt_i32 s61, 0x1b0f
	s_cbranch_scc1 .Ltail_done
	s_lshl_b32 s2, s79, 14
	v_and_b32_e32 v0, 31, v1
	v_lshrrev_b32_e32 v18, 5, v1
	s_add_i32 s2, s2, 0
	v_lshlrev_b32_e32 v2, 2, v0
	v_mul_u32_u24_e32 v4, 0x84, v18
	v_add3_u32 v19, s2, v2, v4
	v_lshlrev_b32_e32 v2, 3, v1
	v_and_b32_e32 v2, 56, v2
	v_mov_b32_e32 v3, 0
	v_mul_u32_u24_e32 v8, 0x84, v2
	v_lshlrev_b32_e32 v2, 1, v2
	v_lshrrev_b32_e32 v20, 3, v1
	v_lshl_add_u64 v[4:5], s[0:1], 0, v[2:3]
	s_mov_b64 s[4:5], 0x1b00000
	v_lshl_add_u64 v[6:7], v[4:5], 0, s[4:5]
	v_lshlrev_b32_e32 v2, 2, v20
	s_mov_b64 s[4:5], 0x1a00000
	v_add3_u32 v21, s2, v8, v2
	v_lshl_add_u64 v[8:9], v[4:5], 0, s[4:5]
	s_mov_b64 s[4:5], 0x1400000
	v_lshl_add_u64 v[10:11], v[4:5], 0, s[4:5]
	s_mov_b64 s[4:5], 0x900000
	s_lshl_b32 s2, s61, 3
	v_lshl_add_u64 v[12:13], v[4:5], 0, s[4:5]
	s_mov_b64 s[4:5], 0x700000
	s_add_i32 s16, s2, 0x780
	s_lshl_b32 s2, s61, 1
	v_add_u32_e32 v22, 8, v20
	v_or_b32_e32 v23, 16, v20
	v_add_u32_e32 v24, 24, v20
	v_lshl_add_u64 v[14:15], v[4:5], 0, s[4:5]
	s_lshl_b32 s14, s61, 5
	s_mov_b32 s15, 0x8000
	s_movk_i32 s17, 0x2000
	s_add_i32 s18, s2, 0xffffd8e0
	s_movk_i32 s19, 0x800
	s_add_i32 s20, 0, 0x23f60
	s_mov_b64 s[4:5], 0x200000
	s_movk_i32 s21, 0x1000
	s_movk_i32 s24, 0x2000
	s_movk_i32 s25, 0x3000
	s_movk_i32 s26, 0x4000
	s_movk_i32 s27, 0x5000
	s_movk_i32 s28, 0x6000
	s_movk_i32 s29, 0x7000
	s_mov_b32 s30, 0x8000
	s_mov_b32 s31, 0x9000
	s_mov_b32 s33, 0xa000
	s_mov_b32 s34, 0xb000
	s_mov_b32 s35, 0xc000
	s_mov_b32 s36, 0xd000
	s_mov_b32 s37, 0xe000
	s_mov_b32 s38, 0xf000
	s_movk_i32 s39, 0x7fff
	s_mov_b32 s40, 0xffff0000
	s_add_i32 s41, 0, 0x23f98
	s_mov_b32 s42, 0x12000
	s_mov_b32 s43, 0x16000
	s_mov_b32 s44, 0x1a000
	s_mov_b32 s45, 0x1e000
	s_mov_b32 s46, 0x22000
	s_mov_b32 s47, 0x26000
	s_mov_b32 s48, 0x2a000
	s_mov_b32 s49, 0x2e000
	s_mov_b32 s50, 0x32000
	s_mov_b32 s51, 0x36000
	s_mov_b32 s52, 0x3a000
	s_mov_b32 s53, 0x3e000
	s_movk_i32 s54, 0x1600
	s_add_i32 s55, 0, 0x23f80
	s_movk_i32 s56, 0x5800
	s_add_i32 s57, 0, 0x23f70
	s_add_i32 s58, 0, 0x23f30
	s_movk_i32 s59, 0xd18
	s_movk_i32 s60, 0x3460
	v_lshlrev_b32_e32 v2, 2, v0
	v_add_u32_e32 v25, 0x400, v19
	v_add_u32_e32 v26, 0x800, v19
	v_add_u32_e32 v27, 0xc00, v19
	v_add_u32_e32 v28, 0x1000, v19
	v_add_u32_e32 v29, 0x1400, v19
	v_add_u32_e32 v30, 0x1800, v19
	v_add_u32_e32 v31, 0x1c00, v19
	s_branch .LBB0_67_t

.LBB0_66_t:
	s_addk_i32 s61, 0x400
	s_add_i32 s14, s14, s15
	s_add_i32 s16, s16, s17
	s_add_i32 s18, s18, s19
	s_cmpk_gt_i32 s61, 0x1b0f
	s_cbranch_scc1 .Ltail_done

.LBB0_152_t:
	s_or_b64 exec, exec, s[12:13]
	s_and_saveexec_b64 s[12:13], vcc
	s_cbranch_execz .LBB0_65_t
	v_add_u32_e32 v32, 62, v32
	v_mad_i64_i32 v[16:17], s[62:63], v32, s60, v[16:17]
	global_load_dword v63, v[16:17], off nt
	s_branch .LBB0_65_t
	s_nop 0
	s_nop 0
	s_nop 0
	s_nop 0
	s_nop 0
	s_nop 0
	s_nop 0
	s_nop 0
	s_nop 0
	s_nop 0
	s_nop 0
	s_nop 0
	s_nop 0
	s_nop 0
	s_nop 0
	s_nop 0
	s_nop 0
	s_nop 0
	s_nop 0
	s_nop 0
	s_nop 0
.Ltail_done:
	s_mov_b64 exec, -1
	v_readlane_b32 s0, v248, 0
	v_readlane_b32 s1, v248, 1
	v_readlane_b32 s10, v248, 2
	v_readlane_b32 s13, v248, 3
	v_readlane_b32 s27, v248, 4
	v_readlane_b32 s28, v248, 5
	v_readlane_b32 s29, v248, 6
	v_readlane_b32 s33, v248, 7
	v_readlane_b32 s42, v248, 8
	v_readlane_b32 s44, v248, 9
	v_readlane_b32 s46, v248, 10
	v_readlane_b32 s47, v248, 11
	v_readlane_b32 s48, v248, 12
	v_readlane_b32 s49, v248, 13
	v_readlane_b32 s50, v248, 14
	v_readlane_b32 s54, v248, 15
	v_readlane_b32 s55, v248, 16
	v_readlane_b32 s56, v248, 17
	v_readlane_b32 s62, v248, 18
	v_readlane_b32 s63, v248, 19
	s_nop 3
.Ltail_skip:
.LBB0_237:
	s_waitcnt vmcnt(0)
	s_waitcnt vmcnt(0) lgkmcnt(0)
	s_barrier
	s_mov_b64 s[2:3], exec
	v_readlane_b32 s4, v247, 4
	v_readlane_b32 s5, v247, 5
	s_and_b64 s[4:5], s[2:3], s[4:5]
	s_mov_b64 exec, s[4:5]
	s_cbranch_execz .LBB0_275
	s_add_i32 s4, 0, 0x23fc0
	v_mov_b32_e32 v0, s4
	s_waitcnt vmcnt(0) expcnt(0) lgkmcnt(0)
	ds_read_b32 v2, v0
	s_add_i32 s4, 0, 0x23fc4
	v_mov_b32_e32 v0, s4
	ds_read_b32 v0, v0
	s_waitcnt lgkmcnt(1)
	v_cmp_ne_u32_e32 vcc, 0, v2
	s_cbranch_vccnz .LBB0_253
	v_readlane_b32 s4, v247, 0
	s_mul_i32 s51, s77, s4
	s_add_u32 s4, s68, 0x2700200
	s_addc_u32 s5, s69, 0
	s_add_u32 s6, s68, 0x2700400
	s_addc_u32 s7, s69, 0
	s_add_u32 s10, s68, 0x2700500
	s_addc_u32 s11, s69, 0
	s_add_u32 s12, s68, 0x2700600
	s_addc_u32 s13, s69, 0
	s_add_u32 s14, s68, 0x2700700
	s_addc_u32 s15, s69, 0
	s_add_u32 s16, s68, 0x2700800
	s_addc_u32 s17, s69, 0
	s_add_u32 s18, s68, 0x2700900
	s_addc_u32 s19, s69, 0
	s_add_u32 s20, s68, 0x2700a00
	s_addc_u32 s21, s69, 0
	s_add_u32 s24, s68, 0x2700b00
	s_addc_u32 s25, s69, 0
	s_add_u32 s26, s68, 0x2700c00
	s_addc_u32 s27, s69, 0
	s_add_u32 s28, s68, 0x2700d00
	s_addc_u32 s29, s69, 0
	s_add_u32 s30, s68, 0x2700e00
	s_addc_u32 s31, s69, 0
	s_add_u32 s34, s68, 0x2700f00
	s_addc_u32 s35, s69, 0
	s_add_u32 s36, s68, 0x2701000
	s_addc_u32 s37, s69, 0
	s_add_u32 s38, s68, 0x2701100
	s_addc_u32 s39, s69, 0
	s_add_u32 s40, s68, 0x2701200
	s_addc_u32 s41, s69, 0
	s_add_u32 s42, s68, 0x2701300
	s_mul_i32 s51, s51, s76
	s_addc_u32 s43, s69, 0
	s_mov_b32 s52, 1
	v_mov_b32_e32 v16, 0
	s_branch .LBB0_241

.Ltail2_p0b:
	s_cmpk_lg_i32 s76, 0x100
	s_cbranch_scc1 .LBB0_371
	v_writelane_b32 v248, s20, 0
	v_writelane_b32 v248, s24, 1
	v_writelane_b32 v248, s25, 2
	v_writelane_b32 v248, s26, 3
	v_writelane_b32 v248, s27, 4
	v_writelane_b32 v248, s42, 5
	v_writelane_b32 v248, s44, 6
	v_writelane_b32 v248, s46, 7
	v_writelane_b32 v248, s47, 8
	v_writelane_b32 v248, s48, 9
	v_writelane_b32 v248, s49, 10
	v_writelane_b32 v248, s50, 11
	v_writelane_b32 v248, s54, 12
	v_writelane_b32 v248, s55, 13
	v_writelane_b32 v248, s56, 14
	s_add_i32 s2, 0, 0x23fa8
	v_mov_b32_e32 v0, s2
	ds_read_b64 v[2:3], v0
	v_mbcnt_lo_u32_b32 v0, -1, 0
	v_mbcnt_hi_u32_b32 v1, -1, v0
	s_waitcnt lgkmcnt(0)
	v_readfirstlane_b32 s0, v2
	v_readfirstlane_b32 s1, v3
	s_mov_b32 s3, 0
	v_readlane_b32 s61, v247, 1
	s_add_i32 s2, s80, 0xffffff80
	s_lshl_b32 s2, s2, 3
	s_lshr_b32 s61, s61, 6
	s_add_i32 s61, s61, s2
	s_addk_i32 s61, 0x800
	s_cmpk_gt_i32 s61, 0x138f
	s_cbranch_scc1 .Ltail2_done
	s_lshl_b32 s2, s79, 14
	v_and_b32_e32 v0, 31, v1
	v_lshrrev_b32_e32 v18, 5, v1
	s_add_i32 s2, s2, 0
	v_lshlrev_b32_e32 v2, 2, v0
	v_mul_u32_u24_e32 v4, 0x84, v18
	v_add3_u32 v19, s2, v2, v4
	v_lshlrev_b32_e32 v2, 3, v1
	v_and_b32_e32 v2, 56, v2
	v_mov_b32_e32 v3, 0
	v_mul_u32_u24_e32 v8, 0x84, v2
	v_lshlrev_b32_e32 v2, 1, v2
	v_lshrrev_b32_e32 v20, 3, v1
	v_lshl_add_u64 v[4:5], s[0:1], 0, v[2:3]
	s_mov_b64 s[4:5], 0x1b00000
	v_lshl_add_u64 v[6:7], v[4:5], 0, s[4:5]
	v_lshlrev_b32_e32 v2, 2, v20
	s_mov_b64 s[4:5], 0x1a00000
	v_add3_u32 v21, s2, v8, v2
	v_lshl_add_u64 v[8:9], v[4:5], 0, s[4:5]
	s_mov_b64 s[4:5], 0x1400000
	v_lshl_add_u64 v[10:11], v[4:5], 0, s[4:5]
	s_mov_b64 s[4:5], 0x900000
	s_lshl_b32 s2, s61, 3
	v_lshl_add_u64 v[12:13], v[4:5], 0, s[4:5]
	s_mov_b64 s[4:5], 0x700000
	s_add_i32 s16, s2, 0x780
	s_lshl_b32 s2, s61, 1
	v_add_u32_e32 v22, 8, v20
	v_or_b32_e32 v23, 16, v20
	v_add_u32_e32 v24, 24, v20
	v_lshl_add_u64 v[14:15], v[4:5], 0, s[4:5]
	s_lshl_b32 s14, s61, 5
	s_mov_b32 s15, 0x8000
	s_movk_i32 s17, 0x2000
	s_add_i32 s18, s2, 0xffffd8e0
	s_movk_i32 s19, 0x800
	s_add_i32 s20, 0, 0x23f60
	s_mov_b64 s[4:5], 0x200000
	s_movk_i32 s21, 0x1000
	s_movk_i32 s24, 0x2000
	s_movk_i32 s25, 0x3000
	s_movk_i32 s26, 0x4000
	s_movk_i32 s27, 0x5000
	s_movk_i32 s28, 0x6000
	s_movk_i32 s29, 0x7000
	s_mov_b32 s30, 0x8000
	s_mov_b32 s31, 0x9000
	s_mov_b32 s33, 0xa000
	s_mov_b32 s34, 0xb000
	s_mov_b32 s35, 0xc000
	s_mov_b32 s36, 0xd000
	s_mov_b32 s37, 0xe000
	s_mov_b32 s38, 0xf000
	s_movk_i32 s39, 0x7fff
	s_mov_b32 s40, 0xffff0000
	s_add_i32 s41, 0, 0x23f98
	s_mov_b32 s42, 0x12000
	s_mov_b32 s43, 0x16000
	s_mov_b32 s44, 0x1a000
	s_mov_b32 s45, 0x1e000
	s_mov_b32 s46, 0x22000
	s_mov_b32 s47, 0x26000
	s_mov_b32 s48, 0x2a000
	s_mov_b32 s49, 0x2e000
	s_mov_b32 s50, 0x32000
	s_mov_b32 s51, 0x36000
	s_mov_b32 s52, 0x3a000
	s_mov_b32 s53, 0x3e000
	s_movk_i32 s54, 0x1600
	s_add_i32 s55, 0, 0x23f80
	s_movk_i32 s56, 0x5800
	s_add_i32 s57, 0, 0x23f70
	s_add_i32 s58, 0, 0x23f30
	s_movk_i32 s59, 0xd18
	s_movk_i32 s60, 0x3460
	v_lshlrev_b32_e32 v2, 2, v0
	v_add_u32_e32 v25, 0x400, v19
	v_add_u32_e32 v26, 0x800, v19
	v_add_u32_e32 v27, 0xc00, v19
	v_add_u32_e32 v28, 0x1000, v19
	v_add_u32_e32 v29, 0x1400, v19
	v_add_u32_e32 v30, 0x1800, v19
	v_add_u32_e32 v31, 0x1c00, v19
	s_branch .LBB0_67_u

.LBB0_66_u:
	s_addk_i32 s61, 0x400
	s_add_i32 s14, s14, s15
	s_add_i32 s16, s16, s17
	s_add_i32 s18, s18, s19
	s_cmpk_gt_i32 s61, 0x138f
	s_cbranch_scc1 .Ltail2_done
